# layer-0 norm1: next input row (read once) loaded with nt
# speedup vs baseline: 1.0039x; 1.0039x over previous
; __device__ __forceinline__ void norm_rows(const Ctx& F, CParams& P, int layer, int which  , int t_first, int t_end, int t_stride) {
;     ...
;     for (int t = t_first; t < t_end; t += t_stride) {
;         const int vs = vsel_of_row(t);
;         const float* shf = mod + (size_t)vs * 12288 + (which ? 3 : 0) * DM; const float* scl = shf + DM;
;         f32x4 v[8], sc[8], sh[8]; float ss = 0.f;
; #pragma unroll
;         for (int j = 0; j < 8; ++j) { v[j] = vn[j]; sc[j] = *(const f32x4*)(scl + j * 256 + lane * 4); sh[j] = *(const f32x4*)(shf + j * 256 + lane * 4); }
;         { const int tn = t + t_stride; const float* src = srcrow(tn < t_end ? tn : t);
; #pragma unroll
;           for (int j = 0; j < 8; ++j) vn[j] = *(const f32x4*)(src + j * 256 + lane * 4); }
; #pragma unroll
;         for (int j = 0; j < 8; ++j) ss += v[j][0] * v[j][0] + v[j][1] * v[j][1] + v[j][2] * v[j][2] + v[j][3] * v[j][3];
;         ss = wave_sum(ss);
;         const float rstd = rsqrtf(ss * (1.f / DM) + EPS);
; #pragma unroll
;         for (int j = 0; j < 8; ++j) { const int c = j * 256 + lane * 4;
;             f32x4 y;
; #pragma unroll
;             for (int e = 0; e < 4; ++e) y[e] = (v[j][e] * rstd * g[j][e]) * (1.f + sc[j][e]) + sh[j][e];
.LBB0_1034:
	s_cmpk_lt_u32 s2, 0x4000
	s_waitcnt vmcnt(0)
	v_mul_f32_e32 v32, v63, v63
	v_mul_f32_e32 v34, v67, v67
	s_cselect_b32 s3, s95, 0x6000
	s_cmpk_gt_i32 s2, 0x1fff
	v_mul_f32_e32 v35, v71, v71
	v_fmac_f32_e32 v32, v62, v62
	v_fmac_f32_e32 v34, v66, v66
	s_cselect_b32 s3, s3, 0
	v_mul_f32_e32 v36, v75, v75
	v_fmac_f32_e32 v35, v70, v70
	v_fmac_f32_e32 v32, v64, v64
	v_fmac_f32_e32 v34, v68, v68
	s_lshl_b32 s3, s3, 2
	v_fmac_f32_e32 v36, v74, v74
	v_fmac_f32_e32 v35, v72, v72
	v_fmac_f32_e32 v32, v65, v65
	v_fmac_f32_e32 v34, v69, v69
	s_add_u32 s16, s10, s3
	v_lshlrev_b64 v[82:83], 2, v[94:95]
	v_fmac_f32_e32 v36, v76, v76
	v_fmac_f32_e32 v35, v73, v73
	v_add_f32_e32 v32, v32, v34
	s_addc_u32 s17, s11, 0
	v_fmac_f32_e32 v36, v77, v77
	v_add_f32_e32 v32, v32, v35
	v_lshl_add_u64 v[50:51], s[16:17], 0, v[82:83]
	v_mul_f32_e32 v40, v79, v79
	v_add_f32_e32 v32, v32, v36
	global_load_dwordx4 v[84:87], v[50:51], off
	global_load_dwordx4 v[34:37], v[50:51], off offset:1024
	v_fmac_f32_e32 v40, v78, v78
	v_add_co_u32_e32 v52, vcc, s95, v50
	v_fmac_f32_e32 v40, v80, v80
	s_nop 0
	v_addc_co_u32_e32 v53, vcc, 0, v51, vcc
	v_fmac_f32_e32 v40, v81, v81
	v_lshl_add_u64 v[38:39], v[50:51], 0, s[42:43]
	v_add_co_u32_e32 v58, vcc, s81, v50
	v_add_f32_e32 v32, v32, v40
	s_nop 0
	v_addc_co_u32_e32 v59, vcc, 0, v51, vcc
	global_load_dwordx4 v[106:109], v[38:39], off offset:1024
	global_load_dwordx4 v[110:113], v[38:39], off offset:2048
	global_load_dwordx4 v[114:117], v[52:53], off offset:-4096
	global_load_dwordx4 v[124:127], v[52:53], off
	global_load_dwordx4 v[128:131], v[38:39], off offset:3072
	s_nop 0
	global_load_dwordx4 v[38:41], v[58:59], off
	global_load_dwordx4 v[132:135], v[52:53], off offset:1024
	global_load_dwordx4 v[136:139], v[52:53], off offset:2048
	global_load_dwordx4 v[140:143], v[52:53], off offset:3072
	v_mul_f32_e32 v54, v47, v47
	v_mul_f32_e32 v55, v43, v43
	v_fmac_f32_e32 v54, v46, v46
	v_mul_f32_e32 v56, v91, v91
	v_fmac_f32_e32 v55, v42, v42
	v_fmac_f32_e32 v54, v48, v48
	v_fmac_f32_e32 v56, v90, v90
	v_fmac_f32_e32 v55, v44, v44
	v_fmac_f32_e32 v54, v49, v49
	v_fmac_f32_e32 v56, v92, v92
	v_fmac_f32_e32 v55, v45, v45
	v_add_f32_e32 v32, v32, v54
	v_fmac_f32_e32 v56, v93, v93
	v_add_f32_e32 v32, v32, v55
	v_add_f32_e32 v32, v32, v56
	ds_swizzle_b32 v52, v32 offset:swizzle(SWAP,16)
	s_add_i32 s7, s2, s6
	s_cmpk_lt_i32 s7, 0x4200
	s_cselect_b64 s[16:17], -1, 0
	s_waitcnt lgkmcnt(0)
	v_add_f32_e32 v32, v32, v52
	ds_swizzle_b32 v52, v32 offset:swizzle(SWAP,8)
	s_waitcnt lgkmcnt(0)
	v_add_f32_e32 v32, v32, v52
	ds_swizzle_b32 v52, v32 offset:swizzle(SWAP,4)
	s_waitcnt lgkmcnt(0)
	v_add_f32_e32 v32, v32, v52
	ds_swizzle_b32 v52, v32 offset:swizzle(SWAP,2)
	s_waitcnt lgkmcnt(0)
	v_add_f32_e32 v32, v32, v52
	ds_swizzle_b32 v52, v32 offset:swizzle(SWAP,1)
	s_waitcnt lgkmcnt(0)
	v_add_f32_e32 v32, v32, v52
	v_mov_b32_e32 v52, v32
	s_nop 1
	v_permlane32_swap_b32_e32 v32, v52
	v_add_f32_e32 v32, v32, v52
	v_fmamk_f32 v32, v32, 0x3a000000, v234
	v_mul_f32_e32 v52, 0x4b800000, v32
	v_cmp_gt_f32_e32 vcc, s57, v32
	s_waitcnt vmcnt(8)
	v_add_f32_e32 v144, 1.0, v106
	v_cndmask_b32_e32 v32, v32, v52, vcc
	v_rsq_f32_e32 v32, v32
	s_waitcnt vmcnt(6)
	v_add_f32_e32 v101, 1.0, v115
	v_add_f32_e32 v102, 1.0, v116
	v_add_f32_e32 v123, 1.0, v117
	v_mul_f32_e32 v52, 0x45800000, v32
	v_cndmask_b32_e32 v32, v32, v52, vcc
	v_mul_f32_e32 v52, v62, v32
	v_mul_f32_e32 v53, v63, v32
	v_mul_f32_e32 v57, v64, v32
	v_mul_f32_e32 v100, v65, v32
	v_mul_f32_e32 v54, v66, v32
	v_mul_f32_e32 v55, v67, v32
	v_mul_f32_e32 v64, v73, v32
	v_mul_f32_e32 v66, v74, v32
	v_mul_f32_e32 v67, v75, v32
	v_mul_f32_e32 v73, v80, v32
	v_mul_f32_e32 v74, v46, v32
	v_mul_f32_e32 v75, v47, v32
	v_mul_f32_e32 v80, v42, v32
	v_mul_f32_e32 v89, v43, v32
	v_mul_f32_e32 v103, v44, v32
	v_mul_f32_e32 v104, v45, v32
	v_add_f32_e32 v46, 1.0, v114
	global_load_dwordx4 v[42:45], v[50:51], off offset:2048
	v_mul_f32_e32 v47, v0, v52
	v_mul_f32_e32 v62, v71, v32
	v_mul_f32_e32 v63, v72, v32
	v_mul_f32_e32 v71, v78, v32
	v_mul_f32_e32 v72, v79, v32
	v_mul_f32_e32 v78, v48, v32
	v_mul_f32_e32 v79, v49, v32
	v_fma_f32 v99, v46, v47, v84
	global_load_dwordx4 v[46:49], v[50:51], off offset:3072
	v_mul_f32_e32 v50, v1, v53
	v_mul_f32_e32 v51, v2, v57
	v_mul_f32_e32 v52, v3, v100
	v_mul_f32_e32 v56, v69, v32
	v_fma_f32 v100, v101, v50, v85
	v_fma_f32 v86, v102, v51, v86
	v_fmac_f32_e32 v87, v123, v52
	global_load_dwordx4 v[50:53], v[58:59], off offset:1024
	v_add_f32_e32 v145, 1.0, v107
	v_add_f32_e32 v146, 1.0, v109
	v_mul_f32_e32 v54, v4, v54
	v_mul_f32_e32 v55, v5, v55
	v_mul_f32_e32 v56, v7, v56
	v_mul_f32_e32 v60, v68, v32
	v_mul_f32_e32 v61, v70, v32
	v_fma_f32 v101, v144, v54, v34
	v_fma_f32 v102, v145, v55, v35
	v_fmac_f32_e32 v37, v146, v56
	global_load_dwordx4 v[54:57], v[58:59], off offset:2048
	v_mul_f32_e32 v34, v6, v60
	v_mul_f32_e32 v35, v8, v61
	global_load_dwordx4 v[58:61], v[58:59], off offset:3072
	s_and_b64 vcc, s[16:17], exec
	s_cselect_b32 s2, s7, s2
	s_add_i32 s15, s2, 0xffffc000
	s_ashr_i32 s3, s2, 31
	s_cmpk_lt_i32 s2, 0x4000
	s_cselect_b32 s3, s3, 0
	s_cselect_b32 s2, s2, s15
	s_cselect_b32 s15, s5, s1
	s_cselect_b32 s16, s4, s0
	s_lshl_b64 s[2:3], s[2:3], 13
	s_add_u32 s2, s16, s2
	v_mul_f32_e32 v70, v76, v32
	v_mul_f32_e32 v76, v81, v32
	v_add_f32_e32 v121, 1.0, v108
	v_add_f32_e32 v122, 1.0, v110
	s_addc_u32 s3, s15, s3
	v_mul_f32_e32 v68, v77, v32
	v_add_f32_e32 v119, 1.0, v112
	s_waitcnt vmcnt(10)
; __device__ __forceinline__ unsigned cvt_pk_bf16(float lo, float hi) { unsigned r; asm("v_cvt_pk_bf16_f32 %0, %1, %2" : "=v"(r) : "v"(lo), "v"(hi)); return r; }
; __device__ __forceinline__ void norm_rows(const Ctx& F, CParams& P, int layer, int which  , int t_first, int t_end, int t_stride) {
;     ...
;         { const int tn = t + t_stride; const float* src = srcrow(tn < t_end ? tn : t);
; #pragma unroll
;           for (int j = 0; j < 8; ++j) vn[j] = *(const f32x4*)(src + j * 256 + lane * 4); }
; #pragma unroll
;         for (int j = 0; j < 8; ++j) ss += v[j][0] * v[j][0] + v[j][1] * v[j][1] + v[j][2] * v[j][2] + v[j][3] * v[j][3];
;         ss = wave_sum(ss);
;         const float rstd = rsqrtf(ss * (1.f / DM) + EPS);
; #pragma unroll
;         for (int j = 0; j < 8; ++j) { const int c = j * 256 + lane * 4;
;             f32x4 y;
; #pragma unroll
;             for (int e = 0; e < 4; ++e) y[e] = (v[j][e] * rstd * g[j][e]) * (1.f + sc[j][e]) + sh[j][e];
;             u32x2 w; w.x = cvt_pk_bf16(y[0], y[1]); w.y = cvt_pk_bf16(y[2], y[3]);
;             *(u32x2*)(H + (size_t)t * DM + c) = w; }
	v_add_f32_e32 v112, 1.0, v127
	v_fma_f32 v36, v121, v34, v36
	v_mul_f32_e32 v76, v19, v76
	v_add_f32_e32 v65, 1.0, v111
	v_add_f32_e32 v120, 1.0, v113
	s_waitcnt vmcnt(9)
	v_add_f32_e32 v69, 1.0, v128
	v_add_f32_e32 v117, 1.0, v129
	v_add_f32_e32 v113, 1.0, v130
	v_add_f32_e32 v118, 1.0, v131
	v_add_f32_e32 v114, 1.0, v124
	v_add_f32_e32 v115, 1.0, v125
	v_add_f32_e32 v116, 1.0, v126
	s_waitcnt vmcnt(7)
	v_add_f32_e32 v77, 1.0, v132
	v_add_f32_e32 v111, 1.0, v133
	v_mul_f32_e32 v62, v9, v62
	v_mul_f32_e32 v63, v10, v63
	v_mul_f32_e32 v64, v11, v64
	v_mul_f32_e32 v66, v12, v66
	v_mul_f32_e32 v67, v13, v67
	v_mul_f32_e32 v68, v15, v68
	v_mul_f32_e32 v70, v14, v70
	v_mul_f32_e32 v71, v16, v71
	v_mul_f32_e32 v72, v17, v72
	v_mul_f32_e32 v73, v18, v73
	v_fmac_f32_e32 v41, v112, v76
	v_mul_f32_e32 v74, v20, v74
	v_mul_f32_e32 v75, v21, v75
	v_add_f32_e32 v81, 1.0, v134
	v_add_f32_e32 v109, 1.0, v135
	v_fma_f32 v38, v114, v71, v38
	s_waitcnt vmcnt(4)
	v_fma_f32 v42, v122, v35, v42
	v_lshl_add_u64 v[34:35], s[2:3], 0, v[82:83]
	v_add_co_u32_e64 v112, s[2:3], s81, v34
	v_fma_f32 v43, v65, v62, v43
	v_fma_f32 v44, v119, v63, v44
	v_fmac_f32_e32 v45, v120, v64
	global_load_dwordx4 v[62:65], v[34:35], off nt
	v_fma_f32 v39, v115, v72, v39
	s_waitcnt vmcnt(4)
	v_fma_f32 v46, v69, v66, v46
	v_fma_f32 v47, v117, v67, v47
	v_fmac_f32_e32 v49, v118, v68
	global_load_dwordx4 v[66:69], v[34:35], off offset:1024 nt
	v_fma_f32 v48, v113, v70, v48
	v_fma_f32 v40, v116, v73, v40
	global_load_dwordx4 v[70:73], v[34:35], off offset:2048 nt
	v_addc_co_u32_e64 v113, s[2:3], 0, v35, s[2:3]
	s_waitcnt vmcnt(5)
	v_fma_f32 v50, v77, v74, v50
	v_fma_f32 v51, v111, v75, v51
	global_load_dwordx4 v[74:77], v[34:35], off offset:3072 nt
	v_mul_f32_e32 v34, v22, v78
	v_mul_f32_e32 v35, v23, v79
	v_mul_f32_e32 v88, v90, v32
	v_add_f32_e32 v110, 1.0, v136
	v_add_f32_e32 v106, 1.0, v137
	v_add_f32_e32 v107, 1.0, v138
	v_add_f32_e32 v108, 1.0, v139
	v_mul_f32_e32 v78, v24, v80
	v_fma_f32 v52, v81, v34, v52
	v_fmac_f32_e32 v53, v109, v35
	v_mul_f32_e32 v34, v25, v89
	v_mul_f32_e32 v35, v26, v103
	v_mul_f32_e32 v82, v27, v104
	v_mul_f32_e32 v90, v91, v32
	v_mul_f32_e32 v91, v92, v32
	v_add_f32_e32 v105, 1.0, v140
	s_waitcnt vmcnt(5)
	v_fma_f32 v54, v110, v78, v54
	global_load_dwordx4 v[78:81], v[112:113], off nt
	v_fma_f32 v55, v106, v34, v55
	v_fma_f32 v56, v107, v35, v56
	v_fmac_f32_e32 v57, v108, v82
	global_load_dwordx4 v[82:85], v[112:113], off offset:1024 nt
	v_mul_f32_e32 v34, v28, v88
	v_cvt_pk_bf16_f32 v35, v86, v87
	global_load_dwordx4 v[86:89], v[112:113], off offset:2048 nt
	v_mul_f32_e32 v98, v93, v32
	v_add_f32_e32 v92, 1.0, v141
	v_add_f32_e32 v93, 1.0, v142
	s_waitcnt vmcnt(7)
	v_fma_f32 v58, v105, v34, v58
	v_mul_f32_e32 v34, v29, v90
	v_mul_f32_e32 v90, v30, v91
	v_fma_f32 v59, v92, v34, v59
	v_fma_f32 v60, v93, v90, v60
	global_load_dwordx4 v[90:93], v[112:113], off offset:3072 nt
	v_add_f32_e32 v32, 1.0, v143
	v_mul_f32_e32 v34, v31, v98
	v_fmac_f32_e32 v61, v32, v34
	v_cvt_pk_bf16_f32 v34, v99, v100
	v_cvt_pk_bf16_f32 v99, v36, v37
	v_cvt_pk_bf16_f32 v36, v42, v43
	v_cvt_pk_bf16_f32 v37, v44, v45
	v_cvt_pk_bf16_f32 v42, v46, v47
	v_cvt_pk_bf16_f32 v43, v48, v49
	v_cvt_pk_bf16_f32 v44, v54, v55
	v_cvt_pk_bf16_f32 v45, v56, v57
	v_cvt_pk_bf16_f32 v46, v58, v59
	v_cvt_pk_bf16_f32 v47, v60, v61
	v_cvt_pk_bf16_f32 v98, v101, v102
	v_cvt_pk_bf16_f32 v38, v38, v39
	v_cvt_pk_bf16_f32 v39, v40, v41
	v_cvt_pk_bf16_f32 v40, v50, v51
	v_cvt_pk_bf16_f32 v41, v52, v53
	global_store_dwordx2 v[96:97], v[34:35], off
	global_store_dwordx2 v[96:97], v[98:99], off offset:512
	global_store_dwordx2 v[96:97], v[36:37], off offset:1024
	global_store_dwordx2 v[96:97], v[42:43], off offset:1536
	global_store_dwordx2 v[96:97], v[38:39], off offset:2048
	global_store_dwordx2 v[96:97], v[40:41], off offset:2560
	global_store_dwordx2 v[96:97], v[44:45], off offset:3072
	global_store_dwordx2 v[96:97], v[46:47], off offset:3584
	s_mov_b32 s2, s7
	v_lshl_add_u64 v[96:97], v[96:97], 0, s[8:9]
	s_waitcnt vmcnt(10)
	v_mov_b64_e32 v[46:47], v[82:83]
	v_mov_b64_e32 v[48:49], v[84:85]
	s_waitcnt vmcnt(9)
	v_mov_b64_e32 v[42:43], v[86:87]
	v_mov_b64_e32 v[44:45], v[88:89]
	s_cbranch_vccnz .LBB0_1034
